# GEMM main loops: each accumulator's two K-halves issued back to back (C forwarding), snake over tiles
# speedup vs baseline: 1.0165x; 1.0152x over previous
.LBB0_120:
	s_add_u32 s28, s40, 0xfff80080
	s_addc_u32 s29, s41, -1
	s_add_i32 s54, 0, 0x10000
	s_cmp_eq_u32 s53, 28
	s_cselect_b32 s29, s23, s29
	s_cselect_b32 s28, s22, s28
	s_cselect_b32 s43, s21, s52
	s_cselect_b32 s42, s50, s51
	s_add_i32 s56, 0, 0x14000
	v_add_u32_e32 v142, s54, v212
	v_add_u32_e32 v158, s56, v212
	ds_read_b128 v[130:133], v142
	ds_read_b128 v[134:137], v142 offset:1024
	ds_read_b128 v[138:141], v142 offset:2048
	ds_read_b128 v[142:145], v142 offset:3072
	ds_read_b128 v[146:149], v158
	ds_read_b128 v[150:153], v158 offset:1024
	ds_read_b128 v[154:157], v158 offset:2048
	ds_read_b128 v[158:161], v158 offset:3072
	v_lshl_add_u64 v[204:205], s[40:41], 0, v[184:185]
	s_add_i32 m0, s24, 0xc000
	ds_read_b128 v[162:165], v213
	ds_read_b128 v[166:169], v213 offset:1024
	ds_read_b128 v[170:173], v213 offset:2048
	ds_read_b128 v[174:177], v213 offset:3072
	ds_read_b128 v[188:191], v213 offset:4096
	ds_read_b128 v[192:195], v213 offset:5120
	ds_read_b128 v[196:199], v213 offset:6144
	ds_read_b128 v[200:203], v213 offset:7168
	global_load_lds_dwordx4 v[204:205], off
	v_lshl_add_u64 v[204:205], s[40:41], 0, v[186:187]
	s_add_i32 m0, s24, 0xe000
	s_nop 0
	global_load_lds_dwordx4 v[204:205], off
	s_waitcnt vmcnt(8)
	s_waitcnt lgkmcnt(0)
	s_barrier
	s_setprio 1
	s_waitcnt lgkmcnt(0)
	v_mfma_f32_16x16x32_bf16 v[126:129], v[130:133], v[162:165], v[126:129]
	v_mfma_f32_16x16x32_bf16 v[126:129], v[134:137], v[166:169], v[126:129]
	v_mfma_f32_16x16x32_bf16 v[122:125], v[142:145], v[166:169], v[122:125]
	v_mfma_f32_16x16x32_bf16 v[122:125], v[138:141], v[162:165], v[122:125]
	v_mfma_f32_16x16x32_bf16 v[106:109], v[138:141], v[170:173], v[106:109]
	v_mfma_f32_16x16x32_bf16 v[106:109], v[142:145], v[174:177], v[106:109]
	v_mfma_f32_16x16x32_bf16 v[110:113], v[134:137], v[174:177], v[110:113]
	v_mfma_f32_16x16x32_bf16 v[110:113], v[130:133], v[170:173], v[110:113]
	v_mfma_f32_16x16x32_bf16 v[94:97], v[130:133], v[188:191], v[94:97]
	v_mfma_f32_16x16x32_bf16 v[94:97], v[134:137], v[192:195], v[94:97]
	v_mfma_f32_16x16x32_bf16 v[90:93], v[142:145], v[192:195], v[90:93]
	v_mfma_f32_16x16x32_bf16 v[90:93], v[138:141], v[188:191], v[90:93]
	v_mfma_f32_16x16x32_bf16 v[74:77], v[138:141], v[196:199], v[74:77]
	v_mfma_f32_16x16x32_bf16 v[74:77], v[142:145], v[200:203], v[74:77]
	v_mfma_f32_16x16x32_bf16 v[78:81], v[134:137], v[200:203], v[78:81]
	v_mfma_f32_16x16x32_bf16 v[78:81], v[130:133], v[196:199], v[78:81]
	s_setprio 0
	s_setprio 1
	v_mfma_f32_16x16x32_bf16 v[118:121], v[146:149], v[162:165], v[118:121]
	v_mfma_f32_16x16x32_bf16 v[118:121], v[150:153], v[166:169], v[118:121]
	v_mfma_f32_16x16x32_bf16 v[114:117], v[158:161], v[166:169], v[114:117]
	v_mfma_f32_16x16x32_bf16 v[114:117], v[154:157], v[162:165], v[114:117]
	v_mfma_f32_16x16x32_bf16 v[98:101], v[154:157], v[170:173], v[98:101]
	v_mfma_f32_16x16x32_bf16 v[98:101], v[158:161], v[174:177], v[98:101]
	v_mfma_f32_16x16x32_bf16 v[102:105], v[150:153], v[174:177], v[102:105]
	v_mfma_f32_16x16x32_bf16 v[102:105], v[146:149], v[170:173], v[102:105]
	v_mfma_f32_16x16x32_bf16 v[86:89], v[146:149], v[188:191], v[86:89]
	v_mfma_f32_16x16x32_bf16 v[86:89], v[150:153], v[192:195], v[86:89]
	v_mfma_f32_16x16x32_bf16 v[82:85], v[158:161], v[192:195], v[82:85]
	v_mfma_f32_16x16x32_bf16 v[82:85], v[154:157], v[188:191], v[82:85]
	v_mfma_f32_16x16x32_bf16 v[66:69], v[154:157], v[196:199], v[66:69]
	v_mfma_f32_16x16x32_bf16 v[66:69], v[158:161], v[200:203], v[66:69]
	v_mfma_f32_16x16x32_bf16 v[70:73], v[150:153], v[200:203], v[70:73]
	v_mfma_f32_16x16x32_bf16 v[70:73], v[146:149], v[196:199], v[70:73]
	s_setprio 0
	s_barrier
	s_add_i32 s54, s54, s1
	v_lshl_add_u64 v[204:205], s[42:43], 0, v[32:33]
	s_mov_b32 m0, s54
	ds_read_b128 v[162:165], v213 offset:16384
	ds_read_b128 v[166:169], v213 offset:17408
	ds_read_b128 v[170:173], v213 offset:18432
	ds_read_b128 v[174:177], v213 offset:19456
	ds_read_b128 v[188:191], v213 offset:20480
	ds_read_b128 v[192:195], v213 offset:21504
	ds_read_b128 v[196:199], v213 offset:22528
	ds_read_b128 v[200:203], v213 offset:23552
	global_load_lds_dwordx4 v[204:205], off
	s_add_i32 m0, s54, 0x2000
	s_add_u32 s54, s42, 0x80000
	v_lshl_add_u64 v[206:207], s[42:43], 0, v[182:183]
	s_addc_u32 s55, s43, 0
	s_add_i32 s56, s56, s1
	global_load_lds_dwordx4 v[206:207], off
	v_lshl_add_u64 v[208:209], s[54:55], 0, v[32:33]
	s_mov_b32 m0, s56
	v_lshl_add_u64 v[214:215], s[28:29], 0, v[180:181]
	global_load_lds_dwordx4 v[208:209], off
	v_lshl_add_u64 v[208:209], s[54:55], 0, v[182:183]
	s_add_i32 m0, s56, 0x2000
	s_nop 0
	global_load_lds_dwordx4 v[208:209], off
	v_lshl_add_u64 v[208:209], s[28:29], 0, v[178:179]
	s_mov_b32 m0, s24
	s_nop 0
	global_load_lds_dwordx4 v[208:209], off
	s_mov_b32 m0, s25
	s_nop 0
	global_load_lds_dwordx4 v[214:215], off
	s_waitcnt vmcnt(8)
	s_waitcnt lgkmcnt(0)
	s_barrier
	s_setprio 1
	s_waitcnt lgkmcnt(0)
	v_mfma_f32_16x16x32_bf16 v[62:65], v[130:133], v[162:165], v[62:65]
	v_mfma_f32_16x16x32_bf16 v[62:65], v[134:137], v[166:169], v[62:65]
	v_mfma_f32_16x16x32_bf16 v[58:61], v[142:145], v[166:169], v[58:61]
	v_mfma_f32_16x16x32_bf16 v[58:61], v[138:141], v[162:165], v[58:61]
	v_mfma_f32_16x16x32_bf16 v[42:45], v[138:141], v[170:173], v[42:45]
	v_mfma_f32_16x16x32_bf16 v[42:45], v[142:145], v[174:177], v[42:45]
	v_mfma_f32_16x16x32_bf16 v[46:49], v[134:137], v[174:177], v[46:49]
	v_mfma_f32_16x16x32_bf16 v[46:49], v[130:133], v[170:173], v[46:49]
	v_mfma_f32_16x16x32_bf16 v[28:31], v[130:133], v[188:191], v[28:31]
	v_mfma_f32_16x16x32_bf16 v[28:31], v[134:137], v[192:195], v[28:31]
	v_mfma_f32_16x16x32_bf16 v[24:27], v[142:145], v[192:195], v[24:27]
	v_mfma_f32_16x16x32_bf16 v[24:27], v[138:141], v[188:191], v[24:27]
	v_mfma_f32_16x16x32_bf16 v[8:11], v[138:141], v[196:199], v[8:11]
	v_mfma_f32_16x16x32_bf16 v[8:11], v[142:145], v[200:203], v[8:11]
	v_mfma_f32_16x16x32_bf16 v[12:15], v[134:137], v[200:203], v[12:15]
	v_mfma_f32_16x16x32_bf16 v[12:15], v[130:133], v[196:199], v[12:15]
	s_setprio 0
	s_setprio 1
	v_mfma_f32_16x16x32_bf16 v[54:57], v[146:149], v[162:165], v[54:57]
	v_mfma_f32_16x16x32_bf16 v[54:57], v[150:153], v[166:169], v[54:57]
	v_mfma_f32_16x16x32_bf16 v[50:53], v[158:161], v[166:169], v[50:53]
	v_mfma_f32_16x16x32_bf16 v[50:53], v[154:157], v[162:165], v[50:53]
	v_mfma_f32_16x16x32_bf16 v[34:37], v[154:157], v[170:173], v[34:37]
	v_mfma_f32_16x16x32_bf16 v[34:37], v[158:161], v[174:177], v[34:37]
	v_mfma_f32_16x16x32_bf16 v[38:41], v[150:153], v[174:177], v[38:41]
	v_mfma_f32_16x16x32_bf16 v[38:41], v[146:149], v[170:173], v[38:41]
	v_mfma_f32_16x16x32_bf16 v[20:23], v[146:149], v[188:191], v[20:23]
	v_mfma_f32_16x16x32_bf16 v[20:23], v[150:153], v[192:195], v[20:23]
	v_mfma_f32_16x16x32_bf16 v[16:19], v[158:161], v[192:195], v[16:19]
	v_mfma_f32_16x16x32_bf16 v[16:19], v[154:157], v[188:191], v[16:19]
	v_mfma_f32_16x16x32_bf16 v[0:3], v[154:157], v[196:199], v[0:3]
	v_mfma_f32_16x16x32_bf16 v[0:3], v[158:161], v[200:203], v[0:3]
	v_mfma_f32_16x16x32_bf16 v[4:7], v[150:153], v[200:203], v[4:7]
	v_mfma_f32_16x16x32_bf16 v[4:7], v[146:149], v[196:199], v[4:7]
	s_setprio 0
	s_barrier
	s_add_i32 s54, 0, 0x18000
	s_add_i32 s55, 0, 0x1c000
	v_add_u32_e32 v142, s54, v212
	v_add_u32_e32 v158, s55, v212
	ds_read_b128 v[130:133], v142
	ds_read_b128 v[134:137], v142 offset:1024
	ds_read_b128 v[138:141], v142 offset:2048
	ds_read_b128 v[142:145], v142 offset:3072
	ds_read_b128 v[146:149], v158
	ds_read_b128 v[150:153], v158 offset:1024
	ds_read_b128 v[154:157], v158 offset:2048
	ds_read_b128 v[158:161], v158 offset:3072
	s_add_u32 s28, s28, 0x80000
	s_addc_u32 s29, s29, 0
	s_mov_b32 m0, s33
	v_lshl_add_u64 v[216:217], s[28:29], 0, v[178:179]
	ds_read_b128 v[162:165], v213 offset:32768
	ds_read_b128 v[166:169], v213 offset:33792
	ds_read_b128 v[170:173], v213 offset:34816
	ds_read_b128 v[174:177], v213 offset:35840
	ds_read_b128 v[188:191], v213 offset:36864
	ds_read_b128 v[192:195], v213 offset:37888
	ds_read_b128 v[196:199], v213 offset:38912
	ds_read_b128 v[200:203], v213 offset:39936
	global_load_lds_dwordx4 v[216:217], off
	v_lshl_add_u64 v[216:217], s[28:29], 0, v[180:181]
	s_mov_b32 m0, s36
	s_nop 0
	global_load_lds_dwordx4 v[216:217], off
	s_waitcnt vmcnt(8)
	s_waitcnt lgkmcnt(0)
	s_barrier
	s_setprio 1
	s_waitcnt lgkmcnt(0)
	v_mfma_f32_16x16x32_bf16 v[126:129], v[130:133], v[162:165], v[126:129]
	v_mfma_f32_16x16x32_bf16 v[126:129], v[134:137], v[166:169], v[126:129]
	v_mfma_f32_16x16x32_bf16 v[122:125], v[142:145], v[166:169], v[122:125]
	v_mfma_f32_16x16x32_bf16 v[122:125], v[138:141], v[162:165], v[122:125]
	v_mfma_f32_16x16x32_bf16 v[106:109], v[138:141], v[170:173], v[106:109]
	v_mfma_f32_16x16x32_bf16 v[106:109], v[142:145], v[174:177], v[106:109]
	v_mfma_f32_16x16x32_bf16 v[110:113], v[134:137], v[174:177], v[110:113]
	v_mfma_f32_16x16x32_bf16 v[110:113], v[130:133], v[170:173], v[110:113]
	v_mfma_f32_16x16x32_bf16 v[94:97], v[130:133], v[188:191], v[94:97]
	v_mfma_f32_16x16x32_bf16 v[94:97], v[134:137], v[192:195], v[94:97]
	v_mfma_f32_16x16x32_bf16 v[90:93], v[142:145], v[192:195], v[90:93]
	v_mfma_f32_16x16x32_bf16 v[90:93], v[138:141], v[188:191], v[90:93]
	v_mfma_f32_16x16x32_bf16 v[74:77], v[138:141], v[196:199], v[74:77]
	v_mfma_f32_16x16x32_bf16 v[74:77], v[142:145], v[200:203], v[74:77]
	v_mfma_f32_16x16x32_bf16 v[78:81], v[134:137], v[200:203], v[78:81]
	v_mfma_f32_16x16x32_bf16 v[78:81], v[130:133], v[196:199], v[78:81]
	s_setprio 0
	s_setprio 1
	v_mfma_f32_16x16x32_bf16 v[118:121], v[146:149], v[162:165], v[118:121]
	v_mfma_f32_16x16x32_bf16 v[118:121], v[150:153], v[166:169], v[118:121]
	v_mfma_f32_16x16x32_bf16 v[114:117], v[158:161], v[166:169], v[114:117]
	v_mfma_f32_16x16x32_bf16 v[114:117], v[154:157], v[162:165], v[114:117]
	v_mfma_f32_16x16x32_bf16 v[98:101], v[154:157], v[170:173], v[98:101]
	v_mfma_f32_16x16x32_bf16 v[98:101], v[158:161], v[174:177], v[98:101]
	v_mfma_f32_16x16x32_bf16 v[102:105], v[150:153], v[174:177], v[102:105]
	v_mfma_f32_16x16x32_bf16 v[102:105], v[146:149], v[170:173], v[102:105]
	v_mfma_f32_16x16x32_bf16 v[86:89], v[146:149], v[188:191], v[86:89]
	v_mfma_f32_16x16x32_bf16 v[86:89], v[150:153], v[192:195], v[86:89]
	v_mfma_f32_16x16x32_bf16 v[82:85], v[158:161], v[192:195], v[82:85]
	v_mfma_f32_16x16x32_bf16 v[82:85], v[154:157], v[188:191], v[82:85]
	v_mfma_f32_16x16x32_bf16 v[66:69], v[154:157], v[196:199], v[66:69]
	v_mfma_f32_16x16x32_bf16 v[66:69], v[158:161], v[200:203], v[66:69]
	v_mfma_f32_16x16x32_bf16 v[70:73], v[150:153], v[200:203], v[70:73]
	v_mfma_f32_16x16x32_bf16 v[70:73], v[146:149], v[196:199], v[70:73]
	s_setprio 0
	s_barrier
	s_add_i32 s28, s54, s1
	v_lshl_add_u64 v[204:205], v[204:205], 0, s[34:35]
	s_mov_b32 m0, s28
	ds_read_b128 v[162:165], v213 offset:49152
	ds_read_b128 v[166:169], v213 offset:50176
	ds_read_b128 v[170:173], v213 offset:51200
	ds_read_b128 v[174:177], v213 offset:52224
	ds_read_b128 v[188:191], v213 offset:53248
	ds_read_b128 v[192:195], v213 offset:54272
	ds_read_b128 v[196:199], v213 offset:55296
	ds_read_b128 v[200:203], v213 offset:56320
	global_load_lds_dwordx4 v[204:205], off
	s_add_i32 m0, s28, 0x2000
	s_add_u32 s28, s42, 0x80080
	v_lshl_add_u64 v[204:205], v[206:207], 0, s[34:35]
	s_addc_u32 s29, s43, 0
	s_add_i32 s42, s55, s1
	global_load_lds_dwordx4 v[204:205], off
	v_lshl_add_u64 v[204:205], s[28:29], 0, v[32:33]
	s_mov_b32 m0, s42
	s_nop 0
	global_load_lds_dwordx4 v[204:205], off
	v_lshl_add_u64 v[204:205], s[28:29], 0, v[182:183]
	s_add_i32 m0, s42, 0x2000
	s_nop 0
	global_load_lds_dwordx4 v[204:205], off
	v_lshl_add_u64 v[204:205], v[208:209], 0, s[34:35]
	s_mov_b32 m0, s44
	s_nop 0
	global_load_lds_dwordx4 v[204:205], off
	v_lshl_add_u64 v[204:205], v[214:215], 0, s[34:35]
	s_mov_b32 m0, s45
	s_nop 0
	global_load_lds_dwordx4 v[204:205], off
	s_waitcnt vmcnt(8)
	s_waitcnt lgkmcnt(0)
	s_barrier
	s_setprio 1
	s_waitcnt lgkmcnt(0)
	v_mfma_f32_16x16x32_bf16 v[62:65], v[130:133], v[162:165], v[62:65]
	v_mfma_f32_16x16x32_bf16 v[62:65], v[134:137], v[166:169], v[62:65]
	v_mfma_f32_16x16x32_bf16 v[58:61], v[142:145], v[166:169], v[58:61]
	v_mfma_f32_16x16x32_bf16 v[58:61], v[138:141], v[162:165], v[58:61]
	v_mfma_f32_16x16x32_bf16 v[42:45], v[138:141], v[170:173], v[42:45]
	v_mfma_f32_16x16x32_bf16 v[42:45], v[142:145], v[174:177], v[42:45]
	v_mfma_f32_16x16x32_bf16 v[46:49], v[134:137], v[174:177], v[46:49]
	v_mfma_f32_16x16x32_bf16 v[46:49], v[130:133], v[170:173], v[46:49]
	v_mfma_f32_16x16x32_bf16 v[28:31], v[130:133], v[188:191], v[28:31]
	v_mfma_f32_16x16x32_bf16 v[28:31], v[134:137], v[192:195], v[28:31]
	v_mfma_f32_16x16x32_bf16 v[24:27], v[142:145], v[192:195], v[24:27]
	v_mfma_f32_16x16x32_bf16 v[24:27], v[138:141], v[188:191], v[24:27]
	v_mfma_f32_16x16x32_bf16 v[8:11], v[138:141], v[196:199], v[8:11]
	v_mfma_f32_16x16x32_bf16 v[8:11], v[142:145], v[200:203], v[8:11]
	v_mfma_f32_16x16x32_bf16 v[12:15], v[134:137], v[200:203], v[12:15]
	v_mfma_f32_16x16x32_bf16 v[12:15], v[130:133], v[196:199], v[12:15]
	s_setprio 0
	s_setprio 1
	v_mfma_f32_16x16x32_bf16 v[54:57], v[146:149], v[162:165], v[54:57]
	v_mfma_f32_16x16x32_bf16 v[54:57], v[150:153], v[166:169], v[54:57]
	v_mfma_f32_16x16x32_bf16 v[50:53], v[158:161], v[166:169], v[50:53]
	v_mfma_f32_16x16x32_bf16 v[50:53], v[154:157], v[162:165], v[50:53]
	v_mfma_f32_16x16x32_bf16 v[34:37], v[154:157], v[170:173], v[34:37]
	v_mfma_f32_16x16x32_bf16 v[34:37], v[158:161], v[174:177], v[34:37]
	v_mfma_f32_16x16x32_bf16 v[38:41], v[150:153], v[174:177], v[38:41]
	v_mfma_f32_16x16x32_bf16 v[38:41], v[146:149], v[170:173], v[38:41]
	v_mfma_f32_16x16x32_bf16 v[20:23], v[146:149], v[188:191], v[20:23]
	v_mfma_f32_16x16x32_bf16 v[20:23], v[150:153], v[192:195], v[20:23]
	v_mfma_f32_16x16x32_bf16 v[16:19], v[158:161], v[192:195], v[16:19]
	v_mfma_f32_16x16x32_bf16 v[16:19], v[154:157], v[188:191], v[16:19]
	v_mfma_f32_16x16x32_bf16 v[0:3], v[154:157], v[196:199], v[0:3]
	v_mfma_f32_16x16x32_bf16 v[0:3], v[158:161], v[200:203], v[0:3]
	v_mfma_f32_16x16x32_bf16 v[4:7], v[150:153], v[200:203], v[4:7]
	v_mfma_f32_16x16x32_bf16 v[4:7], v[146:149], v[196:199], v[4:7]
	s_setprio 0
	s_barrier
	s_add_i32 s53, s53, 2
	s_add_u32 s40, s40, 0x100
	s_addc_u32 s41, s41, 0
	s_add_u32 s51, s51, 0x100
	s_addc_u32 s52, s52, 0
	s_cmp_gt_u32 s53, 29
	s_cbranch_scc0 .LBB0_120
	s_and_b64 vcc, exec, s[18:19]
	s_cbranch_vccz .LBB0_123
	s_barrier

.LBB0_685:
	s_add_u32 s28, s16, s40
	s_addc_u32 s29, s17, s41
	s_add_u32 s28, s28, 0x100
	s_addc_u32 s29, s29, 0
	s_add_u32 s42, s52, s40
	s_addc_u32 s43, s53, s41
	s_add_i32 s56, 0, 0x10000
	s_cmpk_eq_i32 s40, 0xf00
	s_cselect_b32 s29, s39, s29
	s_cselect_b32 s28, s38, s28
	s_cselect_b32 s43, s23, s43
	s_cselect_b32 s42, s54, s42
	s_add_i32 s58, 0, 0x14000
	v_add_u32_e32 v146, s56, v190
	v_add_u32_e32 v162, s58, v190
	ds_read_b128 v[134:137], v146
	ds_read_b128 v[138:141], v146 offset:1024
	ds_read_b128 v[142:145], v146 offset:2048
	ds_read_b128 v[146:149], v146 offset:3072
	ds_read_b128 v[150:153], v162
	ds_read_b128 v[154:157], v162 offset:1024
	ds_read_b128 v[158:161], v162 offset:2048
	ds_read_b128 v[162:165], v162 offset:3072
	v_lshl_add_u64 v[212:213], v[130:131], 0, s[40:41]
	s_add_i32 m0, s24, 0xc000
	ds_read_b128 v[166:169], v191
	ds_read_b128 v[180:183], v191 offset:1024
	ds_read_b128 v[184:187], v191 offset:2048
	ds_read_b128 v[192:195], v191 offset:3072
	ds_read_b128 v[196:199], v191 offset:4096
	ds_read_b128 v[200:203], v191 offset:5120
	ds_read_b128 v[204:207], v191 offset:6144
	ds_read_b128 v[208:211], v191 offset:7168
	global_load_lds_dwordx4 v[212:213], off
	v_lshl_add_u64 v[212:213], v[132:133], 0, s[40:41]
	s_add_i32 m0, s24, 0xe000
	s_nop 0
	global_load_lds_dwordx4 v[212:213], off
	s_waitcnt vmcnt(8)
	s_waitcnt lgkmcnt(0)
	s_barrier
	s_setprio 1
	s_waitcnt lgkmcnt(0)
	v_mfma_f32_16x16x32_bf16 v[82:85], v[134:137], v[166:169], v[82:85]
	v_mfma_f32_16x16x32_bf16 v[82:85], v[138:141], v[180:183], v[82:85]
	v_mfma_f32_16x16x32_bf16 v[78:81], v[146:149], v[180:183], v[78:81]
	v_mfma_f32_16x16x32_bf16 v[78:81], v[142:145], v[166:169], v[78:81]
	v_mfma_f32_16x16x32_bf16 v[70:73], v[142:145], v[184:187], v[70:73]
	v_mfma_f32_16x16x32_bf16 v[70:73], v[146:149], v[192:195], v[70:73]
	v_mfma_f32_16x16x32_bf16 v[74:77], v[138:141], v[192:195], v[74:77]
	v_mfma_f32_16x16x32_bf16 v[74:77], v[134:137], v[184:187], v[74:77]
	v_mfma_f32_16x16x32_bf16 v[66:69], v[134:137], v[196:199], v[66:69]
	v_mfma_f32_16x16x32_bf16 v[66:69], v[138:141], v[200:203], v[66:69]
	v_mfma_f32_16x16x32_bf16 v[62:65], v[146:149], v[200:203], v[62:65]
	v_mfma_f32_16x16x32_bf16 v[62:65], v[142:145], v[196:199], v[62:65]
	v_mfma_f32_16x16x32_bf16 v[54:57], v[142:145], v[204:207], v[54:57]
	v_mfma_f32_16x16x32_bf16 v[54:57], v[146:149], v[208:211], v[54:57]
	v_mfma_f32_16x16x32_bf16 v[58:61], v[138:141], v[208:211], v[58:61]
	v_mfma_f32_16x16x32_bf16 v[58:61], v[134:137], v[204:207], v[58:61]
	s_setprio 0
	s_setprio 1
	v_mfma_f32_16x16x32_bf16 v[50:53], v[150:153], v[166:169], v[50:53]
	v_mfma_f32_16x16x32_bf16 v[50:53], v[154:157], v[180:183], v[50:53]
	v_mfma_f32_16x16x32_bf16 v[46:49], v[162:165], v[180:183], v[46:49]
	v_mfma_f32_16x16x32_bf16 v[46:49], v[158:161], v[166:169], v[46:49]
	v_mfma_f32_16x16x32_bf16 v[38:41], v[158:161], v[184:187], v[38:41]
	v_mfma_f32_16x16x32_bf16 v[38:41], v[162:165], v[192:195], v[38:41]
	v_mfma_f32_16x16x32_bf16 v[42:45], v[154:157], v[192:195], v[42:45]
	v_mfma_f32_16x16x32_bf16 v[42:45], v[150:153], v[184:187], v[42:45]
	v_mfma_f32_16x16x32_bf16 v[34:37], v[150:153], v[196:199], v[34:37]
	v_mfma_f32_16x16x32_bf16 v[34:37], v[154:157], v[200:203], v[34:37]
	v_mfma_f32_16x16x32_bf16 v[28:31], v[162:165], v[200:203], v[28:31]
	v_mfma_f32_16x16x32_bf16 v[28:31], v[158:161], v[196:199], v[28:31]
	v_mfma_f32_16x16x32_bf16 v[20:23], v[158:161], v[204:207], v[20:23]
	v_mfma_f32_16x16x32_bf16 v[20:23], v[162:165], v[208:211], v[20:23]
	v_mfma_f32_16x16x32_bf16 v[24:27], v[154:157], v[208:211], v[24:27]
	v_mfma_f32_16x16x32_bf16 v[24:27], v[150:153], v[204:207], v[24:27]
	s_setprio 0
	s_barrier
	s_add_i32 s56, s56, s13
	v_lshl_add_u64 v[212:213], s[42:43], 0, v[32:33]
	s_mov_b32 m0, s56
	ds_read_b128 v[166:169], v191 offset:16384
	ds_read_b128 v[180:183], v191 offset:17408
	ds_read_b128 v[184:187], v191 offset:18432
	ds_read_b128 v[192:195], v191 offset:19456
	ds_read_b128 v[196:199], v191 offset:20480
	ds_read_b128 v[200:203], v191 offset:21504
	ds_read_b128 v[204:207], v191 offset:22528
	ds_read_b128 v[208:211], v191 offset:23552
	global_load_lds_dwordx4 v[212:213], off
	s_add_i32 m0, s56, 0x2000
	s_add_u32 s56, s42, 0x80000
	v_lshl_add_u64 v[214:215], s[42:43], 0, v[174:175]
	s_addc_u32 s57, s43, 0
	s_add_i32 s58, s58, s13
	global_load_lds_dwordx4 v[214:215], off
	v_lshl_add_u64 v[216:217], s[56:57], 0, v[32:33]
	s_mov_b32 m0, s58
	v_lshl_add_u64 v[220:221], s[28:29], 0, v[172:173]
	global_load_lds_dwordx4 v[216:217], off
	v_lshl_add_u64 v[216:217], s[56:57], 0, v[174:175]
	s_add_i32 m0, s58, 0x2000
	s_nop 0
	global_load_lds_dwordx4 v[216:217], off
	v_lshl_add_u64 v[216:217], s[28:29], 0, v[170:171]
	s_mov_b32 m0, s24
	s_nop 0
	global_load_lds_dwordx4 v[216:217], off
	s_mov_b32 m0, s25
	s_nop 0
	global_load_lds_dwordx4 v[220:221], off
	s_waitcnt vmcnt(8)
	s_waitcnt lgkmcnt(0)
	s_barrier
	s_setprio 1
	s_waitcnt lgkmcnt(0)
	v_mfma_f32_16x16x32_bf16 v[16:19], v[134:137], v[166:169], v[16:19]
	v_mfma_f32_16x16x32_bf16 v[16:19], v[138:141], v[180:183], v[16:19]
	v_mfma_f32_16x16x32_bf16 v[12:15], v[146:149], v[180:183], v[12:15]
	v_mfma_f32_16x16x32_bf16 v[12:15], v[142:145], v[166:169], v[12:15]
	v_mfma_f32_16x16x32_bf16 v[4:7], v[142:145], v[184:187], v[4:7]
	v_mfma_f32_16x16x32_bf16 v[4:7], v[146:149], v[192:195], v[4:7]
	v_mfma_f32_16x16x32_bf16 v[8:11], v[138:141], v[192:195], v[8:11]
	v_mfma_f32_16x16x32_bf16 v[8:11], v[134:137], v[184:187], v[8:11]
	v_mfma_f32_16x16x32_bf16 v[0:3], v[134:137], v[196:199], v[0:3]
	v_mfma_f32_16x16x32_bf16 v[0:3], v[138:141], v[200:203], v[0:3]
	v_mfma_f32_16x16x32_bf16 v[86:89], v[146:149], v[200:203], v[86:89]
	v_mfma_f32_16x16x32_bf16 v[86:89], v[142:145], v[196:199], v[86:89]
	v_mfma_f32_16x16x32_bf16 v[94:97], v[142:145], v[204:207], v[94:97]
	v_mfma_f32_16x16x32_bf16 v[94:97], v[146:149], v[208:211], v[94:97]
	v_mfma_f32_16x16x32_bf16 v[90:93], v[138:141], v[208:211], v[90:93]
	v_mfma_f32_16x16x32_bf16 v[90:93], v[134:137], v[204:207], v[90:93]
	s_setprio 0
	s_setprio 1
	v_mfma_f32_16x16x32_bf16 v[98:101], v[150:153], v[166:169], v[98:101]
	v_mfma_f32_16x16x32_bf16 v[98:101], v[154:157], v[180:183], v[98:101]
	v_mfma_f32_16x16x32_bf16 v[102:105], v[162:165], v[180:183], v[102:105]
	v_mfma_f32_16x16x32_bf16 v[102:105], v[158:161], v[166:169], v[102:105]
	v_mfma_f32_16x16x32_bf16 v[110:113], v[158:161], v[184:187], v[110:113]
	v_mfma_f32_16x16x32_bf16 v[110:113], v[162:165], v[192:195], v[110:113]
	v_mfma_f32_16x16x32_bf16 v[106:109], v[154:157], v[192:195], v[106:109]
	v_mfma_f32_16x16x32_bf16 v[106:109], v[150:153], v[184:187], v[106:109]
	v_mfma_f32_16x16x32_bf16 v[114:117], v[150:153], v[196:199], v[114:117]
	v_mfma_f32_16x16x32_bf16 v[114:117], v[154:157], v[200:203], v[114:117]
	v_mfma_f32_16x16x32_bf16 v[118:121], v[162:165], v[200:203], v[118:121]
	v_mfma_f32_16x16x32_bf16 v[118:121], v[158:161], v[196:199], v[118:121]
	v_mfma_f32_16x16x32_bf16 v[126:129], v[158:161], v[204:207], v[126:129]
	v_mfma_f32_16x16x32_bf16 v[126:129], v[162:165], v[208:211], v[126:129]
	v_mfma_f32_16x16x32_bf16 v[122:125], v[154:157], v[208:211], v[122:125]
	v_mfma_f32_16x16x32_bf16 v[122:125], v[150:153], v[204:207], v[122:125]
	s_setprio 0
	s_barrier
	s_add_i32 s56, 0, 0x18000
	s_add_i32 s57, 0, 0x1c000
	v_add_u32_e32 v146, s56, v190
	v_add_u32_e32 v162, s57, v190
	ds_read_b128 v[134:137], v146
	ds_read_b128 v[138:141], v146 offset:1024
	ds_read_b128 v[142:145], v146 offset:2048
	ds_read_b128 v[146:149], v146 offset:3072
	ds_read_b128 v[150:153], v162
	ds_read_b128 v[154:157], v162 offset:1024
	ds_read_b128 v[158:161], v162 offset:2048
	ds_read_b128 v[162:165], v162 offset:3072
	s_add_u32 s28, s28, 0x80000
	s_addc_u32 s29, s29, 0
	s_mov_b32 m0, s33
	v_lshl_add_u64 v[222:223], s[28:29], 0, v[170:171]
	ds_read_b128 v[166:169], v191 offset:32768
	ds_read_b128 v[180:183], v191 offset:33792
	ds_read_b128 v[184:187], v191 offset:34816
	ds_read_b128 v[192:195], v191 offset:35840
	ds_read_b128 v[196:199], v191 offset:36864
	ds_read_b128 v[200:203], v191 offset:37888
	ds_read_b128 v[204:207], v191 offset:38912
	ds_read_b128 v[208:211], v191 offset:39936
	global_load_lds_dwordx4 v[222:223], off
	v_lshl_add_u64 v[222:223], s[28:29], 0, v[172:173]
	s_mov_b32 m0, s36
	s_nop 0
	global_load_lds_dwordx4 v[222:223], off
	s_waitcnt vmcnt(8)
	s_waitcnt lgkmcnt(0)
	s_barrier
	s_setprio 1
	s_waitcnt lgkmcnt(0)
	v_mfma_f32_16x16x32_bf16 v[82:85], v[134:137], v[166:169], v[82:85]
	v_mfma_f32_16x16x32_bf16 v[82:85], v[138:141], v[180:183], v[82:85]
	v_mfma_f32_16x16x32_bf16 v[78:81], v[146:149], v[180:183], v[78:81]
	v_mfma_f32_16x16x32_bf16 v[78:81], v[142:145], v[166:169], v[78:81]
	v_mfma_f32_16x16x32_bf16 v[70:73], v[142:145], v[184:187], v[70:73]
	v_mfma_f32_16x16x32_bf16 v[70:73], v[146:149], v[192:195], v[70:73]
	v_mfma_f32_16x16x32_bf16 v[74:77], v[138:141], v[192:195], v[74:77]
	v_mfma_f32_16x16x32_bf16 v[74:77], v[134:137], v[184:187], v[74:77]
	v_mfma_f32_16x16x32_bf16 v[66:69], v[134:137], v[196:199], v[66:69]
	v_mfma_f32_16x16x32_bf16 v[66:69], v[138:141], v[200:203], v[66:69]
	v_mfma_f32_16x16x32_bf16 v[62:65], v[146:149], v[200:203], v[62:65]
	v_mfma_f32_16x16x32_bf16 v[62:65], v[142:145], v[196:199], v[62:65]
	v_mfma_f32_16x16x32_bf16 v[54:57], v[142:145], v[204:207], v[54:57]
	v_mfma_f32_16x16x32_bf16 v[54:57], v[146:149], v[208:211], v[54:57]
	v_mfma_f32_16x16x32_bf16 v[58:61], v[138:141], v[208:211], v[58:61]
	v_mfma_f32_16x16x32_bf16 v[58:61], v[134:137], v[204:207], v[58:61]
	s_setprio 0
	s_setprio 1
	v_mfma_f32_16x16x32_bf16 v[50:53], v[150:153], v[166:169], v[50:53]
	v_mfma_f32_16x16x32_bf16 v[50:53], v[154:157], v[180:183], v[50:53]
	v_mfma_f32_16x16x32_bf16 v[46:49], v[162:165], v[180:183], v[46:49]
	v_mfma_f32_16x16x32_bf16 v[46:49], v[158:161], v[166:169], v[46:49]
	v_mfma_f32_16x16x32_bf16 v[38:41], v[158:161], v[184:187], v[38:41]
	v_mfma_f32_16x16x32_bf16 v[38:41], v[162:165], v[192:195], v[38:41]
	v_mfma_f32_16x16x32_bf16 v[42:45], v[154:157], v[192:195], v[42:45]
	v_mfma_f32_16x16x32_bf16 v[42:45], v[150:153], v[184:187], v[42:45]
	v_mfma_f32_16x16x32_bf16 v[34:37], v[150:153], v[196:199], v[34:37]
	v_mfma_f32_16x16x32_bf16 v[34:37], v[154:157], v[200:203], v[34:37]
	v_mfma_f32_16x16x32_bf16 v[28:31], v[162:165], v[200:203], v[28:31]
	v_mfma_f32_16x16x32_bf16 v[28:31], v[158:161], v[196:199], v[28:31]
	v_mfma_f32_16x16x32_bf16 v[20:23], v[158:161], v[204:207], v[20:23]
	v_mfma_f32_16x16x32_bf16 v[20:23], v[162:165], v[208:211], v[20:23]
	v_mfma_f32_16x16x32_bf16 v[24:27], v[154:157], v[208:211], v[24:27]
	v_mfma_f32_16x16x32_bf16 v[24:27], v[150:153], v[204:207], v[24:27]
	s_setprio 0
	s_barrier
	s_add_i32 s28, s56, s13
	v_lshl_add_u64 v[212:213], v[212:213], 0, s[34:35]
	s_mov_b32 m0, s28
	ds_read_b128 v[166:169], v191 offset:49152
	ds_read_b128 v[180:183], v191 offset:50176
	ds_read_b128 v[184:187], v191 offset:51200
	ds_read_b128 v[192:195], v191 offset:52224
	ds_read_b128 v[196:199], v191 offset:53248
	ds_read_b128 v[200:203], v191 offset:54272
	ds_read_b128 v[204:207], v191 offset:55296
	ds_read_b128 v[208:211], v191 offset:56320
	global_load_lds_dwordx4 v[212:213], off
	s_add_i32 m0, s28, 0x2000
	s_add_u32 s28, s42, 0x80080
	v_lshl_add_u64 v[212:213], v[214:215], 0, s[34:35]
	s_addc_u32 s29, s43, 0
	s_add_i32 s42, s57, s13
	global_load_lds_dwordx4 v[212:213], off
	v_lshl_add_u64 v[212:213], s[28:29], 0, v[32:33]
	s_mov_b32 m0, s42
	s_nop 0
	global_load_lds_dwordx4 v[212:213], off
	v_lshl_add_u64 v[212:213], s[28:29], 0, v[174:175]
	s_add_i32 m0, s42, 0x2000
	s_nop 0
	global_load_lds_dwordx4 v[212:213], off
	v_lshl_add_u64 v[212:213], v[216:217], 0, s[34:35]
	s_mov_b32 m0, s45
	s_nop 0
	global_load_lds_dwordx4 v[212:213], off
	v_lshl_add_u64 v[212:213], v[220:221], 0, s[34:35]
	s_mov_b32 m0, s46
	s_nop 0
	global_load_lds_dwordx4 v[212:213], off
	s_waitcnt vmcnt(8)
	s_waitcnt lgkmcnt(0)
	s_barrier
	s_setprio 1
	s_waitcnt lgkmcnt(0)
	v_mfma_f32_16x16x32_bf16 v[16:19], v[134:137], v[166:169], v[16:19]
	v_mfma_f32_16x16x32_bf16 v[16:19], v[138:141], v[180:183], v[16:19]
	v_mfma_f32_16x16x32_bf16 v[12:15], v[146:149], v[180:183], v[12:15]
	v_mfma_f32_16x16x32_bf16 v[12:15], v[142:145], v[166:169], v[12:15]
	v_mfma_f32_16x16x32_bf16 v[4:7], v[142:145], v[184:187], v[4:7]
	v_mfma_f32_16x16x32_bf16 v[4:7], v[146:149], v[192:195], v[4:7]
	v_mfma_f32_16x16x32_bf16 v[8:11], v[138:141], v[192:195], v[8:11]
	v_mfma_f32_16x16x32_bf16 v[8:11], v[134:137], v[184:187], v[8:11]
	v_mfma_f32_16x16x32_bf16 v[0:3], v[134:137], v[196:199], v[0:3]
	v_mfma_f32_16x16x32_bf16 v[0:3], v[138:141], v[200:203], v[0:3]
	v_mfma_f32_16x16x32_bf16 v[86:89], v[146:149], v[200:203], v[86:89]
	v_mfma_f32_16x16x32_bf16 v[86:89], v[142:145], v[196:199], v[86:89]
	v_mfma_f32_16x16x32_bf16 v[94:97], v[142:145], v[204:207], v[94:97]
	v_mfma_f32_16x16x32_bf16 v[94:97], v[146:149], v[208:211], v[94:97]
	v_mfma_f32_16x16x32_bf16 v[90:93], v[138:141], v[208:211], v[90:93]
	v_mfma_f32_16x16x32_bf16 v[90:93], v[134:137], v[204:207], v[90:93]
	s_setprio 0
	s_setprio 1
	v_mfma_f32_16x16x32_bf16 v[98:101], v[150:153], v[166:169], v[98:101]
	v_mfma_f32_16x16x32_bf16 v[98:101], v[154:157], v[180:183], v[98:101]
	v_mfma_f32_16x16x32_bf16 v[102:105], v[162:165], v[180:183], v[102:105]
	v_mfma_f32_16x16x32_bf16 v[102:105], v[158:161], v[166:169], v[102:105]
	v_mfma_f32_16x16x32_bf16 v[110:113], v[158:161], v[184:187], v[110:113]
	v_mfma_f32_16x16x32_bf16 v[110:113], v[162:165], v[192:195], v[110:113]
	v_mfma_f32_16x16x32_bf16 v[106:109], v[154:157], v[192:195], v[106:109]
	v_mfma_f32_16x16x32_bf16 v[106:109], v[150:153], v[184:187], v[106:109]
	v_mfma_f32_16x16x32_bf16 v[114:117], v[150:153], v[196:199], v[114:117]
	v_mfma_f32_16x16x32_bf16 v[114:117], v[154:157], v[200:203], v[114:117]
	v_mfma_f32_16x16x32_bf16 v[118:121], v[162:165], v[200:203], v[118:121]
	v_mfma_f32_16x16x32_bf16 v[118:121], v[158:161], v[196:199], v[118:121]
	v_mfma_f32_16x16x32_bf16 v[126:129], v[158:161], v[204:207], v[126:129]
	v_mfma_f32_16x16x32_bf16 v[126:129], v[162:165], v[208:211], v[126:129]
	v_mfma_f32_16x16x32_bf16 v[122:125], v[154:157], v[208:211], v[122:125]
	v_mfma_f32_16x16x32_bf16 v[122:125], v[150:153], v[204:207], v[122:125]
	s_setprio 0
	s_barrier
	s_add_i32 s55, s55, 2
	s_add_u32 s40, s40, 0x100
	s_addc_u32 s41, s41, 0
	s_cmp_gt_u32 s55, 29
	s_cbranch_scc0 .LBB0_685
	s_and_b64 vcc, exec, s[18:19]
	s_cbranch_vccz .LBB0_688
	s_barrier

.LBB0_755:
	s_add_u32 s6, s4, 0x100
	s_addc_u32 s7, s5, 0
	s_add_i32 s52, 0, 0x10000
	s_cmpk_eq_i32 s51, 0x54
	s_cselect_b32 s29, s23, s7
	s_cselect_b32 s28, s22, s6
	s_cselect_b32 s31, s27, s50
	s_cselect_b32 s30, s26, s33
	s_add_i32 s53, 0, 0x14000
	v_add_u32_e32 v142, s52, v242
	v_add_u32_e32 v158, s53, v242
	ds_read_b128 v[130:133], v142
	ds_read_b128 v[134:137], v142 offset:1024
	ds_read_b128 v[138:141], v142 offset:2048
	ds_read_b128 v[142:145], v142 offset:3072
	ds_read_b128 v[146:149], v158
	ds_read_b128 v[150:153], v158 offset:1024
	ds_read_b128 v[154:157], v158 offset:2048
	ds_read_b128 v[158:161], v158 offset:3072
	v_lshl_add_u64 v[194:195], s[4:5], 0, v[202:203]
	s_add_i32 m0, s36, 0xc000
	ds_read_b128 v[162:165], v243
	ds_read_b128 v[166:169], v243 offset:1024
	ds_read_b128 v[170:173], v243 offset:2048
	ds_read_b128 v[174:177], v243 offset:3072
	ds_read_b128 v[178:181], v243 offset:4096
	ds_read_b128 v[182:185], v243 offset:5120
	ds_read_b128 v[186:189], v243 offset:6144
	ds_read_b128 v[190:193], v243 offset:7168
	global_load_lds_dwordx4 v[194:195], off
	v_lshl_add_u64 v[194:195], s[4:5], 0, v[204:205]
	s_add_i32 m0, s36, 0xe000
	s_nop 0
	global_load_lds_dwordx4 v[194:195], off
	s_waitcnt vmcnt(8)
	s_waitcnt lgkmcnt(0)
	s_barrier
	s_setprio 1
	s_waitcnt lgkmcnt(0)
	v_mfma_f32_16x16x32_bf16 v[126:129], v[130:133], v[162:165], v[126:129]
	v_mfma_f32_16x16x32_bf16 v[126:129], v[134:137], v[166:169], v[126:129]
	v_mfma_f32_16x16x32_bf16 v[122:125], v[142:145], v[166:169], v[122:125]
	v_mfma_f32_16x16x32_bf16 v[122:125], v[138:141], v[162:165], v[122:125]
	v_mfma_f32_16x16x32_bf16 v[106:109], v[138:141], v[170:173], v[106:109]
	v_mfma_f32_16x16x32_bf16 v[106:109], v[142:145], v[174:177], v[106:109]
	v_mfma_f32_16x16x32_bf16 v[110:113], v[134:137], v[174:177], v[110:113]
	v_mfma_f32_16x16x32_bf16 v[110:113], v[130:133], v[170:173], v[110:113]
	v_mfma_f32_16x16x32_bf16 v[94:97], v[130:133], v[178:181], v[94:97]
	v_mfma_f32_16x16x32_bf16 v[94:97], v[134:137], v[182:185], v[94:97]
	v_mfma_f32_16x16x32_bf16 v[90:93], v[142:145], v[182:185], v[90:93]
	v_mfma_f32_16x16x32_bf16 v[90:93], v[138:141], v[178:181], v[90:93]
	v_mfma_f32_16x16x32_bf16 v[74:77], v[138:141], v[186:189], v[74:77]
	v_mfma_f32_16x16x32_bf16 v[74:77], v[142:145], v[190:193], v[74:77]
	v_mfma_f32_16x16x32_bf16 v[78:81], v[134:137], v[190:193], v[78:81]
	v_mfma_f32_16x16x32_bf16 v[78:81], v[130:133], v[186:189], v[78:81]
	s_setprio 0
	s_setprio 1
	v_mfma_f32_16x16x32_bf16 v[118:121], v[146:149], v[162:165], v[118:121]
	v_mfma_f32_16x16x32_bf16 v[118:121], v[150:153], v[166:169], v[118:121]
	v_mfma_f32_16x16x32_bf16 v[114:117], v[158:161], v[166:169], v[114:117]
	v_mfma_f32_16x16x32_bf16 v[114:117], v[154:157], v[162:165], v[114:117]
	v_mfma_f32_16x16x32_bf16 v[98:101], v[154:157], v[170:173], v[98:101]
	v_mfma_f32_16x16x32_bf16 v[98:101], v[158:161], v[174:177], v[98:101]
	v_mfma_f32_16x16x32_bf16 v[102:105], v[150:153], v[174:177], v[102:105]
	v_mfma_f32_16x16x32_bf16 v[102:105], v[146:149], v[170:173], v[102:105]
	v_mfma_f32_16x16x32_bf16 v[86:89], v[146:149], v[178:181], v[86:89]
	v_mfma_f32_16x16x32_bf16 v[86:89], v[150:153], v[182:185], v[86:89]
	v_mfma_f32_16x16x32_bf16 v[82:85], v[158:161], v[182:185], v[82:85]
	v_mfma_f32_16x16x32_bf16 v[82:85], v[154:157], v[178:181], v[82:85]
	v_mfma_f32_16x16x32_bf16 v[66:69], v[154:157], v[186:189], v[66:69]
	v_mfma_f32_16x16x32_bf16 v[66:69], v[158:161], v[190:193], v[66:69]
	v_mfma_f32_16x16x32_bf16 v[70:73], v[150:153], v[190:193], v[70:73]
	v_mfma_f32_16x16x32_bf16 v[70:73], v[146:149], v[186:189], v[70:73]
	s_setprio 0
	s_barrier
	s_add_i32 s4, s52, s1
	v_lshl_add_u64 v[194:195], s[30:31], 0, v[32:33]
	s_mov_b32 m0, s4
	ds_read_b128 v[162:165], v243 offset:16384
	ds_read_b128 v[166:169], v243 offset:17408
	ds_read_b128 v[170:173], v243 offset:18432
	ds_read_b128 v[174:177], v243 offset:19456
	ds_read_b128 v[178:181], v243 offset:20480
	ds_read_b128 v[182:185], v243 offset:21504
	ds_read_b128 v[186:189], v243 offset:22528
	ds_read_b128 v[190:193], v243 offset:23552
	global_load_lds_dwordx4 v[194:195], off
	s_add_i32 m0, s4, 0x2000
	s_add_u32 s4, s30, 0x160000
	v_lshl_add_u64 v[206:207], s[30:31], 0, v[200:201]
	s_addc_u32 s5, s31, 0
	s_add_i32 s52, s53, s1
	global_load_lds_dwordx4 v[206:207], off
	v_lshl_add_u64 v[208:209], s[4:5], 0, v[32:33]
	s_mov_b32 m0, s52
	v_lshl_add_u64 v[210:211], s[28:29], 0, v[198:199]
	global_load_lds_dwordx4 v[208:209], off
	v_lshl_add_u64 v[208:209], s[4:5], 0, v[200:201]
	s_add_i32 m0, s52, 0x2000
	s_nop 0
	global_load_lds_dwordx4 v[208:209], off
	v_lshl_add_u64 v[208:209], s[28:29], 0, v[196:197]
	s_mov_b32 m0, s36
	s_nop 0
	global_load_lds_dwordx4 v[208:209], off
	s_mov_b32 m0, s38
	s_nop 0
	global_load_lds_dwordx4 v[210:211], off
	s_waitcnt vmcnt(8)
	s_waitcnt lgkmcnt(0)
	s_barrier
	s_setprio 1
	s_waitcnt lgkmcnt(0)
	v_mfma_f32_16x16x32_bf16 v[62:65], v[130:133], v[162:165], v[62:65]
	v_mfma_f32_16x16x32_bf16 v[62:65], v[134:137], v[166:169], v[62:65]
	v_mfma_f32_16x16x32_bf16 v[58:61], v[142:145], v[166:169], v[58:61]
	v_mfma_f32_16x16x32_bf16 v[58:61], v[138:141], v[162:165], v[58:61]
	v_mfma_f32_16x16x32_bf16 v[42:45], v[138:141], v[170:173], v[42:45]
	v_mfma_f32_16x16x32_bf16 v[42:45], v[142:145], v[174:177], v[42:45]
	v_mfma_f32_16x16x32_bf16 v[46:49], v[134:137], v[174:177], v[46:49]
	v_mfma_f32_16x16x32_bf16 v[46:49], v[130:133], v[170:173], v[46:49]
	v_mfma_f32_16x16x32_bf16 v[28:31], v[130:133], v[178:181], v[28:31]
	v_mfma_f32_16x16x32_bf16 v[28:31], v[134:137], v[182:185], v[28:31]
	v_mfma_f32_16x16x32_bf16 v[24:27], v[142:145], v[182:185], v[24:27]
	v_mfma_f32_16x16x32_bf16 v[24:27], v[138:141], v[178:181], v[24:27]
	v_mfma_f32_16x16x32_bf16 v[8:11], v[138:141], v[186:189], v[8:11]
	v_mfma_f32_16x16x32_bf16 v[8:11], v[142:145], v[190:193], v[8:11]
	v_mfma_f32_16x16x32_bf16 v[12:15], v[134:137], v[190:193], v[12:15]
	v_mfma_f32_16x16x32_bf16 v[12:15], v[130:133], v[186:189], v[12:15]
	s_setprio 0
	s_setprio 1
	v_mfma_f32_16x16x32_bf16 v[54:57], v[146:149], v[162:165], v[54:57]
	v_mfma_f32_16x16x32_bf16 v[54:57], v[150:153], v[166:169], v[54:57]
	v_mfma_f32_16x16x32_bf16 v[50:53], v[158:161], v[166:169], v[50:53]
	v_mfma_f32_16x16x32_bf16 v[50:53], v[154:157], v[162:165], v[50:53]
	v_mfma_f32_16x16x32_bf16 v[34:37], v[154:157], v[170:173], v[34:37]
	v_mfma_f32_16x16x32_bf16 v[34:37], v[158:161], v[174:177], v[34:37]
	v_mfma_f32_16x16x32_bf16 v[38:41], v[150:153], v[174:177], v[38:41]
	v_mfma_f32_16x16x32_bf16 v[38:41], v[146:149], v[170:173], v[38:41]
	v_mfma_f32_16x16x32_bf16 v[20:23], v[146:149], v[178:181], v[20:23]
	v_mfma_f32_16x16x32_bf16 v[20:23], v[150:153], v[182:185], v[20:23]
	v_mfma_f32_16x16x32_bf16 v[16:19], v[158:161], v[182:185], v[16:19]
	v_mfma_f32_16x16x32_bf16 v[16:19], v[154:157], v[178:181], v[16:19]
	v_mfma_f32_16x16x32_bf16 v[0:3], v[154:157], v[186:189], v[0:3]
	v_mfma_f32_16x16x32_bf16 v[0:3], v[158:161], v[190:193], v[0:3]
	v_mfma_f32_16x16x32_bf16 v[4:7], v[150:153], v[190:193], v[4:7]
	v_mfma_f32_16x16x32_bf16 v[4:7], v[146:149], v[186:189], v[4:7]
	s_setprio 0
	s_barrier
	s_add_i32 s52, 0, 0x18000
	s_add_i32 s53, 0, 0x1c000
	v_add_u32_e32 v142, s52, v242
	v_add_u32_e32 v158, s53, v242
	ds_read_b128 v[130:133], v142
	ds_read_b128 v[134:137], v142 offset:1024
	ds_read_b128 v[138:141], v142 offset:2048
	ds_read_b128 v[142:145], v142 offset:3072
	ds_read_b128 v[146:149], v158
	ds_read_b128 v[150:153], v158 offset:1024
	ds_read_b128 v[154:157], v158 offset:2048
	ds_read_b128 v[158:161], v158 offset:3072
	s_add_u32 s4, s28, 0x160000
	s_addc_u32 s5, s29, 0
	s_mov_b32 m0, s39
	v_lshl_add_u64 v[212:213], s[4:5], 0, v[196:197]
	ds_read_b128 v[162:165], v243 offset:32768
	ds_read_b128 v[166:169], v243 offset:33792
	ds_read_b128 v[170:173], v243 offset:34816
	ds_read_b128 v[174:177], v243 offset:35840
	ds_read_b128 v[178:181], v243 offset:36864
	ds_read_b128 v[182:185], v243 offset:37888
	ds_read_b128 v[186:189], v243 offset:38912
	ds_read_b128 v[190:193], v243 offset:39936
	global_load_lds_dwordx4 v[212:213], off
	v_lshl_add_u64 v[212:213], s[4:5], 0, v[198:199]
	s_mov_b32 m0, s42
	s_nop 0
	global_load_lds_dwordx4 v[212:213], off
	s_waitcnt vmcnt(8)
	s_waitcnt lgkmcnt(0)
	s_barrier
	s_setprio 1
	s_waitcnt lgkmcnt(0)
	v_mfma_f32_16x16x32_bf16 v[126:129], v[130:133], v[162:165], v[126:129]
	v_mfma_f32_16x16x32_bf16 v[126:129], v[134:137], v[166:169], v[126:129]
	v_mfma_f32_16x16x32_bf16 v[122:125], v[142:145], v[166:169], v[122:125]
	v_mfma_f32_16x16x32_bf16 v[122:125], v[138:141], v[162:165], v[122:125]
	v_mfma_f32_16x16x32_bf16 v[106:109], v[138:141], v[170:173], v[106:109]
	v_mfma_f32_16x16x32_bf16 v[106:109], v[142:145], v[174:177], v[106:109]
	v_mfma_f32_16x16x32_bf16 v[110:113], v[134:137], v[174:177], v[110:113]
	v_mfma_f32_16x16x32_bf16 v[110:113], v[130:133], v[170:173], v[110:113]
	v_mfma_f32_16x16x32_bf16 v[94:97], v[130:133], v[178:181], v[94:97]
	v_mfma_f32_16x16x32_bf16 v[94:97], v[134:137], v[182:185], v[94:97]
	v_mfma_f32_16x16x32_bf16 v[90:93], v[142:145], v[182:185], v[90:93]
	v_mfma_f32_16x16x32_bf16 v[90:93], v[138:141], v[178:181], v[90:93]
	v_mfma_f32_16x16x32_bf16 v[74:77], v[138:141], v[186:189], v[74:77]
	v_mfma_f32_16x16x32_bf16 v[74:77], v[142:145], v[190:193], v[74:77]
	v_mfma_f32_16x16x32_bf16 v[78:81], v[134:137], v[190:193], v[78:81]
	v_mfma_f32_16x16x32_bf16 v[78:81], v[130:133], v[186:189], v[78:81]
	s_setprio 0
	s_setprio 1
	v_mfma_f32_16x16x32_bf16 v[118:121], v[146:149], v[162:165], v[118:121]
	v_mfma_f32_16x16x32_bf16 v[118:121], v[150:153], v[166:169], v[118:121]
	v_mfma_f32_16x16x32_bf16 v[114:117], v[158:161], v[166:169], v[114:117]
	v_mfma_f32_16x16x32_bf16 v[114:117], v[154:157], v[162:165], v[114:117]
	v_mfma_f32_16x16x32_bf16 v[98:101], v[154:157], v[170:173], v[98:101]
	v_mfma_f32_16x16x32_bf16 v[98:101], v[158:161], v[174:177], v[98:101]
	v_mfma_f32_16x16x32_bf16 v[102:105], v[150:153], v[174:177], v[102:105]
	v_mfma_f32_16x16x32_bf16 v[102:105], v[146:149], v[170:173], v[102:105]
	v_mfma_f32_16x16x32_bf16 v[86:89], v[146:149], v[178:181], v[86:89]
	v_mfma_f32_16x16x32_bf16 v[86:89], v[150:153], v[182:185], v[86:89]
	v_mfma_f32_16x16x32_bf16 v[82:85], v[158:161], v[182:185], v[82:85]
	v_mfma_f32_16x16x32_bf16 v[82:85], v[154:157], v[178:181], v[82:85]
	v_mfma_f32_16x16x32_bf16 v[66:69], v[154:157], v[186:189], v[66:69]
	v_mfma_f32_16x16x32_bf16 v[66:69], v[158:161], v[190:193], v[66:69]
	v_mfma_f32_16x16x32_bf16 v[70:73], v[150:153], v[190:193], v[70:73]
	v_mfma_f32_16x16x32_bf16 v[70:73], v[146:149], v[186:189], v[70:73]
	s_setprio 0
	s_barrier
	s_add_i32 s4, s52, s1
	v_lshl_add_u64 v[194:195], v[194:195], 0, s[34:35]
	s_mov_b32 m0, s4
	ds_read_b128 v[162:165], v243 offset:49152
	ds_read_b128 v[166:169], v243 offset:50176
	ds_read_b128 v[170:173], v243 offset:51200
	ds_read_b128 v[174:177], v243 offset:52224
	ds_read_b128 v[178:181], v243 offset:53248
	ds_read_b128 v[182:185], v243 offset:54272
	ds_read_b128 v[186:189], v243 offset:55296
	ds_read_b128 v[190:193], v243 offset:56320
	global_load_lds_dwordx4 v[194:195], off
	s_add_i32 m0, s4, 0x2000
	s_add_u32 s4, s30, 0x160080
	v_lshl_add_u64 v[194:195], v[206:207], 0, s[34:35]
	s_addc_u32 s5, s31, 0
	s_add_i32 s28, s53, s1
	global_load_lds_dwordx4 v[194:195], off
	v_lshl_add_u64 v[194:195], s[4:5], 0, v[32:33]
	s_mov_b32 m0, s28
	s_nop 0
	global_load_lds_dwordx4 v[194:195], off
	v_lshl_add_u64 v[194:195], s[4:5], 0, v[200:201]
	s_add_i32 m0, s28, 0x2000
	s_nop 0
	global_load_lds_dwordx4 v[194:195], off
	v_lshl_add_u64 v[194:195], v[208:209], 0, s[34:35]
	s_mov_b32 m0, s44
	s_nop 0
	global_load_lds_dwordx4 v[194:195], off
	v_lshl_add_u64 v[194:195], v[210:211], 0, s[34:35]
	s_mov_b32 m0, s45
	s_nop 0
	global_load_lds_dwordx4 v[194:195], off
	s_waitcnt vmcnt(8)
	s_waitcnt lgkmcnt(0)
	s_barrier
	s_setprio 1
	s_waitcnt lgkmcnt(0)
	v_mfma_f32_16x16x32_bf16 v[62:65], v[130:133], v[162:165], v[62:65]
	v_mfma_f32_16x16x32_bf16 v[62:65], v[134:137], v[166:169], v[62:65]
	v_mfma_f32_16x16x32_bf16 v[58:61], v[142:145], v[166:169], v[58:61]
	v_mfma_f32_16x16x32_bf16 v[58:61], v[138:141], v[162:165], v[58:61]
	v_mfma_f32_16x16x32_bf16 v[42:45], v[138:141], v[170:173], v[42:45]
	v_mfma_f32_16x16x32_bf16 v[42:45], v[142:145], v[174:177], v[42:45]
	v_mfma_f32_16x16x32_bf16 v[46:49], v[134:137], v[174:177], v[46:49]
	v_mfma_f32_16x16x32_bf16 v[46:49], v[130:133], v[170:173], v[46:49]
	v_mfma_f32_16x16x32_bf16 v[28:31], v[130:133], v[178:181], v[28:31]
	v_mfma_f32_16x16x32_bf16 v[28:31], v[134:137], v[182:185], v[28:31]
	v_mfma_f32_16x16x32_bf16 v[24:27], v[142:145], v[182:185], v[24:27]
	v_mfma_f32_16x16x32_bf16 v[24:27], v[138:141], v[178:181], v[24:27]
	v_mfma_f32_16x16x32_bf16 v[8:11], v[138:141], v[186:189], v[8:11]
	v_mfma_f32_16x16x32_bf16 v[8:11], v[142:145], v[190:193], v[8:11]
	v_mfma_f32_16x16x32_bf16 v[12:15], v[134:137], v[190:193], v[12:15]
	v_mfma_f32_16x16x32_bf16 v[12:15], v[130:133], v[186:189], v[12:15]
	s_setprio 0
	s_setprio 1
	v_mfma_f32_16x16x32_bf16 v[54:57], v[146:149], v[162:165], v[54:57]
	v_mfma_f32_16x16x32_bf16 v[54:57], v[150:153], v[166:169], v[54:57]
	v_mfma_f32_16x16x32_bf16 v[50:53], v[158:161], v[166:169], v[50:53]
	v_mfma_f32_16x16x32_bf16 v[50:53], v[154:157], v[162:165], v[50:53]
	v_mfma_f32_16x16x32_bf16 v[34:37], v[154:157], v[170:173], v[34:37]
	v_mfma_f32_16x16x32_bf16 v[34:37], v[158:161], v[174:177], v[34:37]
	v_mfma_f32_16x16x32_bf16 v[38:41], v[150:153], v[174:177], v[38:41]
	v_mfma_f32_16x16x32_bf16 v[38:41], v[146:149], v[170:173], v[38:41]
	v_mfma_f32_16x16x32_bf16 v[20:23], v[146:149], v[178:181], v[20:23]
	v_mfma_f32_16x16x32_bf16 v[20:23], v[150:153], v[182:185], v[20:23]
	v_mfma_f32_16x16x32_bf16 v[16:19], v[158:161], v[182:185], v[16:19]
	v_mfma_f32_16x16x32_bf16 v[16:19], v[154:157], v[178:181], v[16:19]
	v_mfma_f32_16x16x32_bf16 v[0:3], v[154:157], v[186:189], v[0:3]
	v_mfma_f32_16x16x32_bf16 v[0:3], v[158:161], v[190:193], v[0:3]
	v_mfma_f32_16x16x32_bf16 v[4:7], v[150:153], v[190:193], v[4:7]
	v_mfma_f32_16x16x32_bf16 v[4:7], v[146:149], v[186:189], v[4:7]
	s_setprio 0
	s_barrier
	s_add_i32 s51, s51, 2
	s_add_u32 s33, s33, 0x100
	s_addc_u32 s50, s50, 0
	s_cmpk_gt_u32 s51, 0x55
	s_mov_b64 s[4:5], s[6:7]
	s_cbranch_scc0 .LBB0_755
	s_and_b64 vcc, exec, s[18:19]
	s_cbranch_vccz .LBB0_758
	s_barrier

.LBB0_888:
	s_add_u32 s38, s16, s30
	s_addc_u32 s39, s17, s31
	s_add_u32 s38, s38, 0x100
	s_addc_u32 s39, s39, 0
	s_add_u32 s54, s50, s30
	s_addc_u32 s55, s51, s31
	s_add_i32 s56, 0, 0x10000
	s_cmpk_eq_i32 s30, 0xf00
	s_cselect_b32 s41, s29, s39
	s_cselect_b32 s40, s28, s38
	s_cselect_b32 s39, s21, s55
	s_cselect_b32 s38, s52, s54
	s_add_i32 s57, 0, 0x14000
	v_add_u32_e32 v146, s56, v178
	v_add_u32_e32 v172, s57, v178
	ds_read_b128 v[134:137], v146
	ds_read_b128 v[138:141], v146 offset:1024
	ds_read_b128 v[142:145], v146 offset:2048
	ds_read_b128 v[146:149], v146 offset:3072
	ds_read_b128 v[150:153], v172
	ds_read_b128 v[154:157], v172 offset:1024
	ds_read_b128 v[158:161], v172 offset:2048
	ds_read_b128 v[172:175], v172 offset:3072
	v_lshl_add_u64 v[212:213], v[130:131], 0, s[30:31]
	s_add_i32 m0, s24, 0xc000
	ds_read_b128 v[180:183], v179
	ds_read_b128 v[184:187], v179 offset:1024
	ds_read_b128 v[188:191], v179 offset:2048
	ds_read_b128 v[192:195], v179 offset:3072
	ds_read_b128 v[196:199], v179 offset:4096
	ds_read_b128 v[200:203], v179 offset:5120
	ds_read_b128 v[204:207], v179 offset:6144
	ds_read_b128 v[208:211], v179 offset:7168
	global_load_lds_dwordx4 v[212:213], off
	v_lshl_add_u64 v[212:213], v[132:133], 0, s[30:31]
	s_add_i32 m0, s24, 0xe000
	s_nop 0
	global_load_lds_dwordx4 v[212:213], off
	s_waitcnt vmcnt(8)
	s_waitcnt lgkmcnt(0)
	s_barrier
	s_setprio 1
	s_waitcnt lgkmcnt(0)
	v_mfma_f32_16x16x32_bf16 v[82:85], v[134:137], v[180:183], v[82:85]
	v_mfma_f32_16x16x32_bf16 v[82:85], v[138:141], v[184:187], v[82:85]
	v_mfma_f32_16x16x32_bf16 v[78:81], v[146:149], v[184:187], v[78:81]
	v_mfma_f32_16x16x32_bf16 v[78:81], v[142:145], v[180:183], v[78:81]
	v_mfma_f32_16x16x32_bf16 v[70:73], v[142:145], v[188:191], v[70:73]
	v_mfma_f32_16x16x32_bf16 v[70:73], v[146:149], v[192:195], v[70:73]
	v_mfma_f32_16x16x32_bf16 v[74:77], v[138:141], v[192:195], v[74:77]
	v_mfma_f32_16x16x32_bf16 v[74:77], v[134:137], v[188:191], v[74:77]
	v_mfma_f32_16x16x32_bf16 v[66:69], v[134:137], v[196:199], v[66:69]
	v_mfma_f32_16x16x32_bf16 v[66:69], v[138:141], v[200:203], v[66:69]
	v_mfma_f32_16x16x32_bf16 v[62:65], v[146:149], v[200:203], v[62:65]
	v_mfma_f32_16x16x32_bf16 v[62:65], v[142:145], v[196:199], v[62:65]
	v_mfma_f32_16x16x32_bf16 v[54:57], v[142:145], v[204:207], v[54:57]
	v_mfma_f32_16x16x32_bf16 v[54:57], v[146:149], v[208:211], v[54:57]
	v_mfma_f32_16x16x32_bf16 v[58:61], v[138:141], v[208:211], v[58:61]
	v_mfma_f32_16x16x32_bf16 v[58:61], v[134:137], v[204:207], v[58:61]
	s_setprio 0
	s_setprio 1
	v_mfma_f32_16x16x32_bf16 v[50:53], v[150:153], v[180:183], v[50:53]
	v_mfma_f32_16x16x32_bf16 v[50:53], v[154:157], v[184:187], v[50:53]
	v_mfma_f32_16x16x32_bf16 v[46:49], v[172:175], v[184:187], v[46:49]
	v_mfma_f32_16x16x32_bf16 v[46:49], v[158:161], v[180:183], v[46:49]
	v_mfma_f32_16x16x32_bf16 v[38:41], v[158:161], v[188:191], v[38:41]
	v_mfma_f32_16x16x32_bf16 v[38:41], v[172:175], v[192:195], v[38:41]
	v_mfma_f32_16x16x32_bf16 v[42:45], v[154:157], v[192:195], v[42:45]
	v_mfma_f32_16x16x32_bf16 v[42:45], v[150:153], v[188:191], v[42:45]
	v_mfma_f32_16x16x32_bf16 v[34:37], v[150:153], v[196:199], v[34:37]
	v_mfma_f32_16x16x32_bf16 v[34:37], v[154:157], v[200:203], v[34:37]
	v_mfma_f32_16x16x32_bf16 v[28:31], v[172:175], v[200:203], v[28:31]
	v_mfma_f32_16x16x32_bf16 v[28:31], v[158:161], v[196:199], v[28:31]
	v_mfma_f32_16x16x32_bf16 v[20:23], v[158:161], v[204:207], v[20:23]
	v_mfma_f32_16x16x32_bf16 v[20:23], v[172:175], v[208:211], v[20:23]
	v_mfma_f32_16x16x32_bf16 v[24:27], v[154:157], v[208:211], v[24:27]
	v_mfma_f32_16x16x32_bf16 v[24:27], v[150:153], v[204:207], v[24:27]
	s_setprio 0
	s_barrier
	s_add_i32 s54, s56, s13
	v_lshl_add_u64 v[212:213], s[38:39], 0, v[32:33]
	s_mov_b32 m0, s54
	ds_read_b128 v[180:183], v179 offset:16384
	ds_read_b128 v[184:187], v179 offset:17408
	ds_read_b128 v[188:191], v179 offset:18432
	ds_read_b128 v[192:195], v179 offset:19456
	ds_read_b128 v[196:199], v179 offset:20480
	ds_read_b128 v[200:203], v179 offset:21504
	ds_read_b128 v[204:207], v179 offset:22528
	ds_read_b128 v[208:211], v179 offset:23552
	global_load_lds_dwordx4 v[212:213], off
	s_add_i32 m0, s54, 0x2000
	s_add_u32 s54, s38, 0x80000
	v_lshl_add_u64 v[214:215], s[38:39], 0, v[166:167]
	s_addc_u32 s55, s39, 0
	s_add_i32 s56, s57, s13
	global_load_lds_dwordx4 v[214:215], off
	v_lshl_add_u64 v[216:217], s[54:55], 0, v[32:33]
	s_mov_b32 m0, s56
	v_lshl_add_u64 v[220:221], s[40:41], 0, v[164:165]
	global_load_lds_dwordx4 v[216:217], off
	v_lshl_add_u64 v[216:217], s[54:55], 0, v[166:167]
	s_add_i32 m0, s56, 0x2000
	s_nop 0
	global_load_lds_dwordx4 v[216:217], off
	v_lshl_add_u64 v[216:217], s[40:41], 0, v[162:163]
	s_mov_b32 m0, s24
	s_nop 0
	global_load_lds_dwordx4 v[216:217], off
	s_mov_b32 m0, s25
	s_nop 0
	global_load_lds_dwordx4 v[220:221], off
	s_waitcnt vmcnt(8)
	s_waitcnt lgkmcnt(0)
	s_barrier
	s_setprio 1
	s_waitcnt lgkmcnt(0)
	v_mfma_f32_16x16x32_bf16 v[16:19], v[134:137], v[180:183], v[16:19]
	v_mfma_f32_16x16x32_bf16 v[16:19], v[138:141], v[184:187], v[16:19]
	v_mfma_f32_16x16x32_bf16 v[12:15], v[146:149], v[184:187], v[12:15]
	v_mfma_f32_16x16x32_bf16 v[12:15], v[142:145], v[180:183], v[12:15]
	v_mfma_f32_16x16x32_bf16 v[4:7], v[142:145], v[188:191], v[4:7]
	v_mfma_f32_16x16x32_bf16 v[4:7], v[146:149], v[192:195], v[4:7]
	v_mfma_f32_16x16x32_bf16 v[8:11], v[138:141], v[192:195], v[8:11]
	v_mfma_f32_16x16x32_bf16 v[8:11], v[134:137], v[188:191], v[8:11]
	v_mfma_f32_16x16x32_bf16 v[0:3], v[134:137], v[196:199], v[0:3]
	v_mfma_f32_16x16x32_bf16 v[0:3], v[138:141], v[200:203], v[0:3]
	v_mfma_f32_16x16x32_bf16 v[86:89], v[146:149], v[200:203], v[86:89]
	v_mfma_f32_16x16x32_bf16 v[86:89], v[142:145], v[196:199], v[86:89]
	v_mfma_f32_16x16x32_bf16 v[94:97], v[142:145], v[204:207], v[94:97]
	v_mfma_f32_16x16x32_bf16 v[94:97], v[146:149], v[208:211], v[94:97]
	v_mfma_f32_16x16x32_bf16 v[90:93], v[138:141], v[208:211], v[90:93]
	v_mfma_f32_16x16x32_bf16 v[90:93], v[134:137], v[204:207], v[90:93]
	s_setprio 0
	s_setprio 1
	v_mfma_f32_16x16x32_bf16 v[98:101], v[150:153], v[180:183], v[98:101]
	v_mfma_f32_16x16x32_bf16 v[98:101], v[154:157], v[184:187], v[98:101]
	v_mfma_f32_16x16x32_bf16 v[102:105], v[172:175], v[184:187], v[102:105]
	v_mfma_f32_16x16x32_bf16 v[102:105], v[158:161], v[180:183], v[102:105]
	v_mfma_f32_16x16x32_bf16 v[110:113], v[158:161], v[188:191], v[110:113]
	v_mfma_f32_16x16x32_bf16 v[110:113], v[172:175], v[192:195], v[110:113]
	v_mfma_f32_16x16x32_bf16 v[106:109], v[154:157], v[192:195], v[106:109]
	v_mfma_f32_16x16x32_bf16 v[106:109], v[150:153], v[188:191], v[106:109]
	v_mfma_f32_16x16x32_bf16 v[114:117], v[150:153], v[196:199], v[114:117]
	v_mfma_f32_16x16x32_bf16 v[114:117], v[154:157], v[200:203], v[114:117]
	v_mfma_f32_16x16x32_bf16 v[118:121], v[172:175], v[200:203], v[118:121]
	v_mfma_f32_16x16x32_bf16 v[118:121], v[158:161], v[196:199], v[118:121]
	v_mfma_f32_16x16x32_bf16 v[126:129], v[158:161], v[204:207], v[126:129]
	v_mfma_f32_16x16x32_bf16 v[126:129], v[172:175], v[208:211], v[126:129]
	v_mfma_f32_16x16x32_bf16 v[122:125], v[154:157], v[208:211], v[122:125]
	v_mfma_f32_16x16x32_bf16 v[122:125], v[150:153], v[204:207], v[122:125]
	s_setprio 0
	s_barrier
	s_add_i32 s54, 0, 0x18000
	s_add_i32 s55, 0, 0x1c000
	v_add_u32_e32 v146, s54, v178
	v_add_u32_e32 v172, s55, v178
	ds_read_b128 v[134:137], v146
	ds_read_b128 v[138:141], v146 offset:1024
	ds_read_b128 v[142:145], v146 offset:2048
	ds_read_b128 v[146:149], v146 offset:3072
	ds_read_b128 v[150:153], v172
	ds_read_b128 v[154:157], v172 offset:1024
	ds_read_b128 v[158:161], v172 offset:2048
	ds_read_b128 v[172:175], v172 offset:3072
	s_add_u32 s40, s40, 0x80000
	s_addc_u32 s41, s41, 0
	s_mov_b32 m0, s33
	v_lshl_add_u64 v[222:223], s[40:41], 0, v[162:163]
	ds_read_b128 v[180:183], v179 offset:32768
	ds_read_b128 v[184:187], v179 offset:33792
	ds_read_b128 v[188:191], v179 offset:34816
	ds_read_b128 v[192:195], v179 offset:35840
	ds_read_b128 v[196:199], v179 offset:36864
	ds_read_b128 v[200:203], v179 offset:37888
	ds_read_b128 v[204:207], v179 offset:38912
	ds_read_b128 v[208:211], v179 offset:39936
	global_load_lds_dwordx4 v[222:223], off
	v_lshl_add_u64 v[222:223], s[40:41], 0, v[164:165]
	s_mov_b32 m0, s36
	s_nop 0
	global_load_lds_dwordx4 v[222:223], off
	s_waitcnt vmcnt(8)
	s_waitcnt lgkmcnt(0)
	s_barrier
	s_setprio 1
	s_waitcnt lgkmcnt(0)
	v_mfma_f32_16x16x32_bf16 v[82:85], v[134:137], v[180:183], v[82:85]
	v_mfma_f32_16x16x32_bf16 v[82:85], v[138:141], v[184:187], v[82:85]
	v_mfma_f32_16x16x32_bf16 v[78:81], v[146:149], v[184:187], v[78:81]
	v_mfma_f32_16x16x32_bf16 v[78:81], v[142:145], v[180:183], v[78:81]
	v_mfma_f32_16x16x32_bf16 v[70:73], v[142:145], v[188:191], v[70:73]
	v_mfma_f32_16x16x32_bf16 v[70:73], v[146:149], v[192:195], v[70:73]
	v_mfma_f32_16x16x32_bf16 v[74:77], v[138:141], v[192:195], v[74:77]
	v_mfma_f32_16x16x32_bf16 v[74:77], v[134:137], v[188:191], v[74:77]
	v_mfma_f32_16x16x32_bf16 v[66:69], v[134:137], v[196:199], v[66:69]
	v_mfma_f32_16x16x32_bf16 v[66:69], v[138:141], v[200:203], v[66:69]
	v_mfma_f32_16x16x32_bf16 v[62:65], v[146:149], v[200:203], v[62:65]
	v_mfma_f32_16x16x32_bf16 v[62:65], v[142:145], v[196:199], v[62:65]
	v_mfma_f32_16x16x32_bf16 v[54:57], v[142:145], v[204:207], v[54:57]
	v_mfma_f32_16x16x32_bf16 v[54:57], v[146:149], v[208:211], v[54:57]
	v_mfma_f32_16x16x32_bf16 v[58:61], v[138:141], v[208:211], v[58:61]
	v_mfma_f32_16x16x32_bf16 v[58:61], v[134:137], v[204:207], v[58:61]
	s_setprio 0
	s_setprio 1
	v_mfma_f32_16x16x32_bf16 v[50:53], v[150:153], v[180:183], v[50:53]
	v_mfma_f32_16x16x32_bf16 v[50:53], v[154:157], v[184:187], v[50:53]
	v_mfma_f32_16x16x32_bf16 v[46:49], v[172:175], v[184:187], v[46:49]
	v_mfma_f32_16x16x32_bf16 v[46:49], v[158:161], v[180:183], v[46:49]
	v_mfma_f32_16x16x32_bf16 v[38:41], v[158:161], v[188:191], v[38:41]
	v_mfma_f32_16x16x32_bf16 v[38:41], v[172:175], v[192:195], v[38:41]
	v_mfma_f32_16x16x32_bf16 v[42:45], v[154:157], v[192:195], v[42:45]
	v_mfma_f32_16x16x32_bf16 v[42:45], v[150:153], v[188:191], v[42:45]
	v_mfma_f32_16x16x32_bf16 v[34:37], v[150:153], v[196:199], v[34:37]
	v_mfma_f32_16x16x32_bf16 v[34:37], v[154:157], v[200:203], v[34:37]
	v_mfma_f32_16x16x32_bf16 v[28:31], v[172:175], v[200:203], v[28:31]
	v_mfma_f32_16x16x32_bf16 v[28:31], v[158:161], v[196:199], v[28:31]
	v_mfma_f32_16x16x32_bf16 v[20:23], v[158:161], v[204:207], v[20:23]
	v_mfma_f32_16x16x32_bf16 v[20:23], v[172:175], v[208:211], v[20:23]
	v_mfma_f32_16x16x32_bf16 v[24:27], v[154:157], v[208:211], v[24:27]
	v_mfma_f32_16x16x32_bf16 v[24:27], v[150:153], v[204:207], v[24:27]
	s_setprio 0
	s_barrier
	s_add_i32 s40, s54, s13
	v_lshl_add_u64 v[212:213], v[212:213], 0, s[34:35]
	s_mov_b32 m0, s40
	ds_read_b128 v[180:183], v179 offset:49152
	ds_read_b128 v[184:187], v179 offset:50176
	ds_read_b128 v[188:191], v179 offset:51200
	ds_read_b128 v[192:195], v179 offset:52224
	ds_read_b128 v[196:199], v179 offset:53248
	ds_read_b128 v[200:203], v179 offset:54272
	ds_read_b128 v[204:207], v179 offset:55296
	ds_read_b128 v[208:211], v179 offset:56320
	global_load_lds_dwordx4 v[212:213], off
	s_add_i32 m0, s40, 0x2000
	s_add_u32 s38, s38, 0x80080
	v_lshl_add_u64 v[212:213], v[214:215], 0, s[34:35]
	s_addc_u32 s39, s39, 0
	s_add_i32 s40, s55, s13
	global_load_lds_dwordx4 v[212:213], off
	v_lshl_add_u64 v[212:213], s[38:39], 0, v[32:33]
	s_mov_b32 m0, s40
	s_nop 0
	global_load_lds_dwordx4 v[212:213], off
	v_lshl_add_u64 v[212:213], s[38:39], 0, v[166:167]
	s_add_i32 m0, s40, 0x2000
	s_nop 0
	global_load_lds_dwordx4 v[212:213], off
	v_lshl_add_u64 v[212:213], v[216:217], 0, s[34:35]
	s_mov_b32 m0, s43
	s_nop 0
	global_load_lds_dwordx4 v[212:213], off
	v_lshl_add_u64 v[212:213], v[220:221], 0, s[34:35]
	s_mov_b32 m0, s44
	s_nop 0
	global_load_lds_dwordx4 v[212:213], off
	s_waitcnt vmcnt(8)
	s_waitcnt lgkmcnt(0)
	s_barrier
	s_setprio 1
	s_waitcnt lgkmcnt(0)
	v_mfma_f32_16x16x32_bf16 v[16:19], v[134:137], v[180:183], v[16:19]
	v_mfma_f32_16x16x32_bf16 v[16:19], v[138:141], v[184:187], v[16:19]
	v_mfma_f32_16x16x32_bf16 v[12:15], v[146:149], v[184:187], v[12:15]
	v_mfma_f32_16x16x32_bf16 v[12:15], v[142:145], v[180:183], v[12:15]
	v_mfma_f32_16x16x32_bf16 v[4:7], v[142:145], v[188:191], v[4:7]
	v_mfma_f32_16x16x32_bf16 v[4:7], v[146:149], v[192:195], v[4:7]
	v_mfma_f32_16x16x32_bf16 v[8:11], v[138:141], v[192:195], v[8:11]
	v_mfma_f32_16x16x32_bf16 v[8:11], v[134:137], v[188:191], v[8:11]
	v_mfma_f32_16x16x32_bf16 v[0:3], v[134:137], v[196:199], v[0:3]
	v_mfma_f32_16x16x32_bf16 v[0:3], v[138:141], v[200:203], v[0:3]
	v_mfma_f32_16x16x32_bf16 v[86:89], v[146:149], v[200:203], v[86:89]
	v_mfma_f32_16x16x32_bf16 v[86:89], v[142:145], v[196:199], v[86:89]
	v_mfma_f32_16x16x32_bf16 v[94:97], v[142:145], v[204:207], v[94:97]
	v_mfma_f32_16x16x32_bf16 v[94:97], v[146:149], v[208:211], v[94:97]
	v_mfma_f32_16x16x32_bf16 v[90:93], v[138:141], v[208:211], v[90:93]
	v_mfma_f32_16x16x32_bf16 v[90:93], v[134:137], v[204:207], v[90:93]
	s_setprio 0
	s_setprio 1
	v_mfma_f32_16x16x32_bf16 v[98:101], v[150:153], v[180:183], v[98:101]
	v_mfma_f32_16x16x32_bf16 v[98:101], v[154:157], v[184:187], v[98:101]
	v_mfma_f32_16x16x32_bf16 v[102:105], v[172:175], v[184:187], v[102:105]
	v_mfma_f32_16x16x32_bf16 v[102:105], v[158:161], v[180:183], v[102:105]
	v_mfma_f32_16x16x32_bf16 v[110:113], v[158:161], v[188:191], v[110:113]
	v_mfma_f32_16x16x32_bf16 v[110:113], v[172:175], v[192:195], v[110:113]
	v_mfma_f32_16x16x32_bf16 v[106:109], v[154:157], v[192:195], v[106:109]
	v_mfma_f32_16x16x32_bf16 v[106:109], v[150:153], v[188:191], v[106:109]
	v_mfma_f32_16x16x32_bf16 v[114:117], v[150:153], v[196:199], v[114:117]
	v_mfma_f32_16x16x32_bf16 v[114:117], v[154:157], v[200:203], v[114:117]
	v_mfma_f32_16x16x32_bf16 v[118:121], v[172:175], v[200:203], v[118:121]
	v_mfma_f32_16x16x32_bf16 v[118:121], v[158:161], v[196:199], v[118:121]
	v_mfma_f32_16x16x32_bf16 v[126:129], v[158:161], v[204:207], v[126:129]
	v_mfma_f32_16x16x32_bf16 v[126:129], v[172:175], v[208:211], v[126:129]
	v_mfma_f32_16x16x32_bf16 v[122:125], v[154:157], v[208:211], v[122:125]
	v_mfma_f32_16x16x32_bf16 v[122:125], v[150:153], v[204:207], v[122:125]
	s_setprio 0
	s_barrier
	s_add_i32 s53, s53, 2
	s_add_u32 s30, s30, 0x100
	s_addc_u32 s31, s31, 0
	s_cmp_gt_u32 s53, 29
	s_cbranch_scc0 .LBB0_888
	s_and_b64 vcc, exec, s[18:19]
	s_cbranch_vccz .LBB0_891
	s_barrier
